# also: no nt hint on P5 epilogue x loads and P11 x1b loads
# baseline (speedup 1.0000x reference)
.LBB0_589:
	s_ashr_i32 s19, s50, 31
	s_lshr_b32 s19, s19, 27
	s_add_i32 s19, s50, s19
	s_ashr_i32 s19, s19, 5
	v_lshl_or_b32 v144, s24, 8, v174
	s_mul_hi_i32 s25, s19, 0x6000
	s_mulk_i32 s19, 0x6000
	s_add_u32 s26, s39, s19
	v_ashrrev_i32_e32 v145, 31, v144
	s_addc_u32 s27, s40, s25
	v_lshlrev_b64 v[196:197], 2, v[144:145]
	v_lshl_add_u64 v[234:235], s[26:27], 0, v[196:197]
	v_lshl_add_u64 v[146:147], s[8:9], 0, v[196:197]
	global_load_dwordx4 v[156:159], v[234:235], off offset:16
	global_load_dwordx4 v[148:151], v[234:235], off
	global_load_dwordx4 v[160:163], v[146:147], off offset:16
	global_load_dwordx4 v[152:155], v[146:147], off
	v_lshl_add_u32 v146, s50, 8, v172
	v_ashrrev_i32_e32 v147, 31, v146
	v_lshlrev_b64 v[164:165], 10, v[146:147]
	v_lshl_add_u64 v[214:215], v[164:165], 0, v[144:145]
	s_add_u32 s24, s41, s19
	v_lshl_add_u64 v[246:247], v[214:215], 2, s[52:53]
	s_addc_u32 s25, s42, s25
	global_load_dwordx4 v[164:167], v[246:247], off offset:16
	global_load_dwordx4 v[168:171], v[246:247], off
	v_lshl_add_u64 v[192:193], s[10:11], 0, v[196:197]
	v_lshl_add_u64 v[242:243], s[24:25], 0, v[196:197]
	global_load_dwordx4 v[180:183], v[192:193], off
	global_load_dwordx4 v[184:187], v[242:243], off
	global_load_dwordx4 v[188:191], v[242:243], off offset:16
	s_nop 0
	global_load_dwordx4 v[192:195], v[192:193], off offset:16
	v_lshl_add_u64 v[210:211], s[78:79], 0, v[196:197]
	global_load_dwordx4 v[196:199], v[210:211], off
	global_load_dwordx4 v[200:203], v[210:211], off offset:16
	v_or_b32_e32 v204, 0x80, v144
	v_or_b32_e32 v206, 0x84, v144
	v_ashrrev_i32_e32 v205, 31, v204
	v_ashrrev_i32_e32 v207, 31, v206
	v_lshlrev_b64 v[216:217], 2, v[204:205]
	v_lshl_add_u64 v[226:227], v[206:207], 2, s[8:9]
	v_lshl_add_u64 v[218:219], s[8:9], 0, v[216:217]
	v_lshl_add_u64 v[222:223], s[10:11], 0, v[216:217]
	v_lshlrev_b64 v[230:231], 1, v[214:215]
	global_load_dwordx4 v[204:207], v[210:211], off offset:528
	s_nop 0
	global_load_dwordx4 v[210:213], v[210:211], off offset:512
	s_nop 0
	global_load_dwordx4 v[214:217], v[218:219], off
	s_nop 0
	global_load_dwordx4 v[218:221], v[222:223], off
	s_nop 0
	global_load_dwordx4 v[222:225], v[222:223], off offset:16
	s_nop 0
	global_load_dwordx4 v[226:229], v[226:227], off
	v_lshl_add_u64 v[248:249], s[14:15], 0, v[230:231]
	v_lshl_add_u64 v[250:251], s[94:95], 0, v[230:231]
	global_load_dwordx4 v[230:233], v[234:235], off offset:528
	s_nop 0
	global_load_dwordx4 v[234:237], v[234:235], off offset:512
	s_nop 0
	global_load_dwordx4 v[238:241], v[242:243], off offset:528
	s_nop 0
	global_load_dwordx4 v[242:245], v[242:243], off offset:512
	s_waitcnt vmcnt(0)
	v_pk_add_f32 v[150:151], v[150:151], v[154:155]
	v_pk_add_f32 v[154:155], v[148:149], v[152:153]
	v_pk_add_f32 v[148:149], v[158:159], v[162:163]
	v_pk_add_f32 v[152:153], v[156:157], v[160:161]
	v_pk_fma_f32 v[252:253], v[122:123], v[148:149], v[166:167]
	v_pk_fma_f32 v[160:161], v[126:127], v[150:151], v[170:171]
	v_pk_fma_f32 v[162:163], v[124:125], v[154:155], v[168:169]
	v_pk_add_f32 v[124:125], v[186:187], v[182:183]
	v_pk_add_f32 v[126:127], v[184:185], v[180:181]
	v_pk_fma_f32 v[208:209], v[120:121], v[152:153], v[164:165]
	v_pk_add_f32 v[156:157], v[190:191], v[194:195]
	v_pk_add_f32 v[158:159], v[188:189], v[192:193]
	v_cvt_pk_bf16_f32 v120, v162, v163
	v_cvt_pk_bf16_f32 v121, v160, v161
	v_cvt_pk_bf16_f32 v122, v208, v209
	v_cvt_pk_bf16_f32 v123, v252, v253
	v_pk_add_f32 v[124:125], v[124:125], 1.0 op_sel_hi:[1,0]
	v_pk_add_f32 v[126:127], v[126:127], 1.0 op_sel_hi:[1,0]
	v_pk_add_f32 v[156:157], v[156:157], 1.0 op_sel_hi:[1,0]
	v_pk_add_f32 v[158:159], v[158:159], 1.0 op_sel_hi:[1,0]
	global_store_dwordx4 v[248:249], v[120:123], off
	v_pk_mul_f32 v[126:127], v[196:197], v[126:127]
	v_pk_add_f32 v[168:169], v[236:237], v[216:217]
	v_pk_mul_f32 v[122:123], v[198:199], v[124:125]
	v_pk_mul_f32 v[120:121], v[202:203], v[156:157]
	v_pk_mul_f32 v[124:125], v[200:201], v[158:159]
	v_pk_mul_f32 v[158:159], v[122:123], v[160:161]
	v_pk_mul_f32 v[156:157], v[126:127], v[162:163]
	v_pk_mul_f32 v[164:165], v[120:121], v[252:253]
	v_pk_mul_f32 v[166:167], v[124:125], v[208:209]
	v_cvt_pk_bf16_f32 v156, v156, v157
	v_cvt_pk_bf16_f32 v157, v158, v159
	v_pk_add_f32 v[170:171], v[234:235], v[214:215]
	v_cvt_pk_bf16_f32 v158, v166, v167
	v_cvt_pk_bf16_f32 v159, v164, v165
	global_store_dwordx4 v[250:251], v[156:159], off
	global_load_dwordx4 v[180:183], v[246:247], off offset:512
	global_load_dwordx4 v[184:187], v[246:247], off offset:528
	v_and_b32_e32 v157, 64, v178
	v_xor_b32_e32 v156, 16, v178
	v_add_u32_e32 v157, 64, v157
	v_xor_b32_e32 v158, 32, v178
	v_cmp_lt_i32_e32 vcc, v156, v157
	v_pk_add_f32 v[188:189], v[240:241], v[224:225]
	v_pk_add_f32 v[190:191], v[238:239], v[222:223]
	v_cndmask_b32_e32 v156, v178, v156, vcc
	v_cmp_lt_i32_e32 vcc, v158, v157
	v_lshlrev_b32_e32 v179, 2, v156
	v_pk_add_f32 v[156:157], v[244:245], v[220:221]
	v_cndmask_b32_e32 v192, v178, v158, vcc
	v_pk_add_f32 v[158:159], v[242:243], v[218:219]
	v_pk_add_f32 v[166:167], v[230:231], v[226:227]
	v_mul_f32_e32 v193, v163, v163
	v_mul_f32_e32 v194, v161, v161
	v_pk_add_f32 v[156:157], v[156:157], 1.0 op_sel_hi:[1,0]
	v_pk_add_f32 v[158:159], v[158:159], 1.0 op_sel_hi:[1,0]
	v_pk_add_f32 v[188:189], v[188:189], 1.0 op_sel_hi:[1,0]
	v_pk_add_f32 v[190:191], v[190:191], 1.0 op_sel_hi:[1,0]
	v_pk_add_f32 v[164:165], v[232:233], v[228:229]
	v_fmac_f32_e32 v193, v162, v162
	v_fmac_f32_e32 v194, v160, v160
	v_pk_mul_f32 v[162:163], v[212:213], v[156:157]
	v_pk_mul_f32 v[160:161], v[210:211], v[158:159]
	v_pk_mul_f32 v[156:157], v[206:207], v[188:189]
	v_pk_mul_f32 v[158:159], v[204:205], v[190:191]
	v_mul_f32_e32 v195, v209, v209
	v_mul_f32_e32 v196, v253, v253
	v_fmac_f32_e32 v195, v208, v208
	v_add_f32_e32 v188, v193, v194
	v_fmac_f32_e32 v196, v252, v252
	v_add_f32_e32 v188, v188, v195
	v_add_f32_e32 v188, v196, v188
	s_waitcnt vmcnt(1)
	v_pk_fma_f32 v[118:119], v[118:119], v[168:169], v[182:183]
	v_pk_fma_f32 v[116:117], v[116:117], v[170:171], v[180:181]
	s_waitcnt vmcnt(0)
	v_pk_fma_f32 v[182:183], v[112:113], v[166:167], v[184:185]
	v_mul_f32_e32 v189, v117, v117
	v_mul_f32_e32 v190, v119, v119
	v_pk_fma_f32 v[180:181], v[114:115], v[164:165], v[186:187]
	v_mul_f32_e32 v191, v183, v183
	v_fmac_f32_e32 v189, v116, v116
	v_fmac_f32_e32 v190, v118, v118
	v_cvt_pk_bf16_f32 v112, v116, v117
	v_mul_f32_e32 v193, v181, v181
	v_pk_mul_f32 v[186:187], v[160:161], v[116:117]
	v_fmac_f32_e32 v191, v182, v182
	v_add_f32_e32 v116, v189, v190
	v_fmac_f32_e32 v193, v180, v180
	v_add_f32_e32 v116, v116, v191
	v_add_f32_e32 v116, v193, v116
	v_add_f32_e32 v117, v188, v116
	ds_bpermute_b32 v188, v179, v117
	v_cvt_pk_bf16_f32 v113, v118, v119
	v_cvt_pk_bf16_f32 v114, v182, v183
	v_cvt_pk_bf16_f32 v115, v180, v181
	global_store_dwordx4 v[248:249], v[112:115], off offset:256
	v_pk_mul_f32 v[184:185], v[162:163], v[118:119]
	v_pk_mul_f32 v[118:119], v[158:159], v[182:183]
	s_waitcnt lgkmcnt(0)
	v_add_f32_e32 v112, v117, v188
	v_lshlrev_b32_e32 v114, 2, v192
	ds_bpermute_b32 v113, v114, v112
	v_pk_mul_f32 v[180:181], v[156:157], v[180:181]
	v_cvt_pk_bf16_f32 v116, v186, v187
	v_cvt_pk_bf16_f32 v117, v184, v185
	v_cvt_pk_bf16_f32 v118, v118, v119
	s_nop 0
	v_cvt_pk_bf16_f32 v119, v180, v181
	global_store_dwordx4 v[250:251], v[116:119], off offset:256
	s_and_saveexec_b64 s[24:25], s[4:5]
	s_cbranch_execz .LBB0_591
	v_lshl_add_u64 v[116:117], v[146:147], 2, s[96:97]
	s_waitcnt lgkmcnt(0)
	v_add_f32_e32 v112, v112, v113
	global_atomic_add_f32 v[116:117], v112, off
.LBB0_591:
	s_or_b64 exec, exec, s[24:25]
	v_or_b32_e32 v112, 16, v146
	s_waitcnt lgkmcnt(0)
	v_ashrrev_i32_e32 v113, 31, v112
	v_lshlrev_b64 v[116:117], 10, v[112:113]
	v_lshl_add_u64 v[184:185], v[116:117], 0, v[144:145]
	v_lshl_add_u64 v[186:187], v[184:185], 2, s[52:53]
	global_load_dwordx4 v[116:119], v[186:187], off
	global_load_dwordx4 v[180:183], v[186:187], off offset:16
	v_lshlrev_b64 v[184:185], 1, v[184:185]
	v_lshl_add_u64 v[188:189], s[14:15], 0, v[184:185]
	v_lshl_add_u64 v[184:185], s[94:95], 0, v[184:185]
	s_waitcnt vmcnt(1)
	v_pk_fma_f32 v[118:119], v[110:111], v[150:151], v[118:119]
	v_pk_fma_f32 v[116:117], v[108:109], v[154:155], v[116:117]
	s_waitcnt vmcnt(0)
	v_pk_fma_f32 v[182:183], v[106:107], v[148:149], v[182:183]
	v_pk_fma_f32 v[180:181], v[104:105], v[152:153], v[180:181]
	v_cvt_pk_bf16_f32 v104, v116, v117
	v_cvt_pk_bf16_f32 v105, v118, v119
	v_pk_mul_f32 v[108:109], v[122:123], v[118:119]
	v_cvt_pk_bf16_f32 v106, v180, v181
	v_cvt_pk_bf16_f32 v107, v182, v183
	v_pk_mul_f32 v[110:111], v[126:127], v[116:117]
	v_pk_mul_f32 v[190:191], v[120:121], v[182:183]
	v_pk_mul_f32 v[192:193], v[124:125], v[180:181]
	global_store_dwordx4 v[188:189], v[104:107], off
	v_mul_f32_e32 v115, v117, v117
	v_mul_f32_e32 v117, v119, v119
	v_cvt_pk_bf16_f32 v104, v110, v111
	v_cvt_pk_bf16_f32 v105, v108, v109
	v_cvt_pk_bf16_f32 v106, v192, v193
	v_cvt_pk_bf16_f32 v107, v190, v191
	global_store_dwordx4 v[184:185], v[104:107], off
	global_load_dwordx4 v[104:107], v[186:187], off offset:512
	s_nop 0
	global_load_dwordx4 v[108:111], v[186:187], off offset:528
	v_mul_f32_e32 v119, v181, v181
	v_fmac_f32_e32 v115, v116, v116
	v_fmac_f32_e32 v117, v118, v118
	v_mul_f32_e32 v147, v183, v183
	v_fmac_f32_e32 v119, v180, v180
	v_add_f32_e32 v115, v115, v117
	v_fmac_f32_e32 v147, v182, v182
	v_add_f32_e32 v115, v119, v115
	v_add_f32_e32 v115, v147, v115
	s_waitcnt vmcnt(1)
	v_pk_fma_f32 v[102:103], v[102:103], v[168:169], v[106:107]
	v_pk_fma_f32 v[100:101], v[100:101], v[170:171], v[104:105]
	s_waitcnt vmcnt(0)
	v_pk_fma_f32 v[106:107], v[96:97], v[166:167], v[108:109]
	v_mul_f32_e32 v108, v101, v101
	v_mul_f32_e32 v109, v103, v103
	v_pk_fma_f32 v[104:105], v[98:99], v[164:165], v[110:111]
	v_cvt_pk_bf16_f32 v96, v100, v101
	v_mul_f32_e32 v110, v107, v107
	v_fmac_f32_e32 v108, v100, v100
	v_fmac_f32_e32 v109, v102, v102
	v_cvt_pk_bf16_f32 v97, v102, v103
	v_cvt_pk_bf16_f32 v98, v106, v107
	v_cvt_pk_bf16_f32 v99, v104, v105
	v_mul_f32_e32 v111, v105, v105
	global_store_dwordx4 v[188:189], v[96:99], off offset:256
	v_fmac_f32_e32 v110, v106, v106
	v_fmac_f32_e32 v111, v104, v104
	v_add_f32_e32 v96, v108, v109
	v_add_f32_e32 v96, v96, v110
	v_add_f32_e32 v96, v111, v96
	v_add_f32_e32 v99, v115, v96
	ds_bpermute_b32 v108, v179, v99
	v_pk_mul_f32 v[96:97], v[160:161], v[100:101]
	v_pk_mul_f32 v[100:101], v[158:159], v[106:107]
	v_cvt_pk_bf16_f32 v98, v96, v97
	v_pk_mul_f32 v[102:103], v[162:163], v[102:103]
	s_waitcnt lgkmcnt(0)
	v_add_f32_e32 v96, v99, v108
	ds_bpermute_b32 v97, v114, v96
	v_pk_mul_f32 v[104:105], v[156:157], v[104:105]
	v_cvt_pk_bf16_f32 v99, v102, v103
	v_cvt_pk_bf16_f32 v100, v100, v101
	s_nop 0
	v_cvt_pk_bf16_f32 v101, v104, v105
	global_store_dwordx4 v[184:185], v[98:101], off offset:256
	s_and_saveexec_b64 s[24:25], s[4:5]
	s_cbranch_execz .LBB0_593
	v_lshl_add_u64 v[98:99], v[112:113], 2, s[96:97]
	s_waitcnt lgkmcnt(0)
	v_add_f32_e32 v96, v96, v97
	global_atomic_add_f32 v[98:99], v96, off
.LBB0_593:
	s_or_b64 exec, exec, s[24:25]
	v_or_b32_e32 v96, 32, v146
	s_waitcnt lgkmcnt(0)
	v_ashrrev_i32_e32 v97, 31, v96
	v_lshlrev_b64 v[98:99], 10, v[96:97]
	v_lshl_add_u64 v[106:107], v[98:99], 0, v[144:145]
	v_lshl_add_u64 v[108:109], v[106:107], 2, s[52:53]
	global_load_dwordx4 v[98:101], v[108:109], off
	global_load_dwordx4 v[102:105], v[108:109], off offset:16
	v_lshlrev_b64 v[106:107], 1, v[106:107]
	v_lshl_add_u64 v[110:111], s[14:15], 0, v[106:107]
	v_lshl_add_u64 v[106:107], s[94:95], 0, v[106:107]
	s_waitcnt vmcnt(1)
	v_pk_fma_f32 v[100:101], v[94:95], v[150:151], v[100:101]
	v_pk_fma_f32 v[98:99], v[92:93], v[154:155], v[98:99]
	s_waitcnt vmcnt(0)
	v_pk_fma_f32 v[104:105], v[90:91], v[148:149], v[104:105]
	v_pk_fma_f32 v[102:103], v[88:89], v[152:153], v[102:103]
	v_cvt_pk_bf16_f32 v88, v98, v99
	v_cvt_pk_bf16_f32 v89, v100, v101
	v_pk_mul_f32 v[92:93], v[122:123], v[100:101]
	v_cvt_pk_bf16_f32 v90, v102, v103
	v_cvt_pk_bf16_f32 v91, v104, v105
	v_pk_mul_f32 v[94:95], v[126:127], v[98:99]
	v_pk_mul_f32 v[112:113], v[120:121], v[104:105]
	v_pk_mul_f32 v[116:117], v[124:125], v[102:103]
	global_store_dwordx4 v[110:111], v[88:91], off
	v_mul_f32_e32 v99, v99, v99
	v_mul_f32_e32 v101, v101, v101
	v_cvt_pk_bf16_f32 v88, v94, v95
	v_cvt_pk_bf16_f32 v89, v92, v93
	v_cvt_pk_bf16_f32 v90, v116, v117
	v_cvt_pk_bf16_f32 v91, v112, v113
	global_store_dwordx4 v[106:107], v[88:91], off
	global_load_dwordx4 v[88:91], v[108:109], off offset:512
	s_nop 0
	global_load_dwordx4 v[92:95], v[108:109], off offset:528
	v_mul_f32_e32 v103, v103, v103
	v_fmac_f32_e32 v99, v98, v98
	v_fmac_f32_e32 v101, v100, v100
	v_mul_f32_e32 v105, v105, v105
	v_fmac_f32_e32 v103, v102, v102
	v_add_f32_e32 v98, v99, v101
	v_fmac_f32_e32 v105, v104, v104
	v_add_f32_e32 v98, v103, v98
	v_add_f32_e32 v98, v105, v98
	s_waitcnt vmcnt(1)
	v_pk_fma_f32 v[86:87], v[86:87], v[168:169], v[90:91]
	v_pk_fma_f32 v[84:85], v[84:85], v[170:171], v[88:89]
	s_waitcnt vmcnt(0)
	v_pk_fma_f32 v[90:91], v[80:81], v[166:167], v[92:93]
	v_mul_f32_e32 v92, v85, v85
	v_mul_f32_e32 v93, v87, v87
	v_pk_fma_f32 v[88:89], v[82:83], v[164:165], v[94:95]
	v_cvt_pk_bf16_f32 v80, v84, v85
	v_mul_f32_e32 v94, v91, v91
	v_fmac_f32_e32 v92, v84, v84
	v_fmac_f32_e32 v93, v86, v86
	v_cvt_pk_bf16_f32 v81, v86, v87
	v_cvt_pk_bf16_f32 v82, v90, v91
	v_cvt_pk_bf16_f32 v83, v88, v89
	v_mul_f32_e32 v95, v89, v89
	global_store_dwordx4 v[110:111], v[80:83], off offset:256
	v_fmac_f32_e32 v94, v90, v90
	v_fmac_f32_e32 v95, v88, v88
	v_add_f32_e32 v80, v92, v93
	v_add_f32_e32 v80, v80, v94
	v_add_f32_e32 v80, v95, v80
	v_add_f32_e32 v83, v98, v80
	ds_bpermute_b32 v92, v179, v83
	v_pk_mul_f32 v[80:81], v[160:161], v[84:85]
	v_pk_mul_f32 v[84:85], v[158:159], v[90:91]
	v_cvt_pk_bf16_f32 v82, v80, v81
	v_pk_mul_f32 v[86:87], v[162:163], v[86:87]
	s_waitcnt lgkmcnt(0)
	v_add_f32_e32 v80, v83, v92
	ds_bpermute_b32 v81, v114, v80
	v_pk_mul_f32 v[88:89], v[156:157], v[88:89]
	v_cvt_pk_bf16_f32 v83, v86, v87
	v_cvt_pk_bf16_f32 v84, v84, v85
	s_nop 0
	v_cvt_pk_bf16_f32 v85, v88, v89
	global_store_dwordx4 v[106:107], v[82:85], off offset:256
	s_and_saveexec_b64 s[24:25], s[4:5]
	s_cbranch_execz .LBB0_595
	v_lshl_add_u64 v[82:83], v[96:97], 2, s[96:97]
	s_waitcnt lgkmcnt(0)
	v_add_f32_e32 v80, v80, v81
	global_atomic_add_f32 v[82:83], v80, off
.LBB0_595:
	s_or_b64 exec, exec, s[24:25]
	v_or_b32_e32 v80, 48, v146
	s_waitcnt lgkmcnt(0)
	v_ashrrev_i32_e32 v81, 31, v80
	v_lshlrev_b64 v[82:83], 10, v[80:81]
	v_lshl_add_u64 v[90:91], v[82:83], 0, v[144:145]
	v_lshl_add_u64 v[92:93], v[90:91], 2, s[52:53]
	global_load_dwordx4 v[82:85], v[92:93], off
	global_load_dwordx4 v[86:89], v[92:93], off offset:16
	v_lshlrev_b64 v[90:91], 1, v[90:91]
	v_lshl_add_u64 v[94:95], s[14:15], 0, v[90:91]
	v_lshl_add_u64 v[90:91], s[94:95], 0, v[90:91]
	s_waitcnt vmcnt(1)
	v_pk_fma_f32 v[84:85], v[78:79], v[150:151], v[84:85]
	v_pk_fma_f32 v[82:83], v[76:77], v[154:155], v[82:83]
	s_waitcnt vmcnt(0)
	v_pk_fma_f32 v[88:89], v[74:75], v[148:149], v[88:89]
	v_pk_fma_f32 v[86:87], v[72:73], v[152:153], v[86:87]
	v_cvt_pk_bf16_f32 v72, v82, v83
	v_cvt_pk_bf16_f32 v73, v84, v85
	v_pk_mul_f32 v[76:77], v[122:123], v[84:85]
	v_cvt_pk_bf16_f32 v74, v86, v87
	v_cvt_pk_bf16_f32 v75, v88, v89
	v_pk_mul_f32 v[78:79], v[126:127], v[82:83]
	v_pk_mul_f32 v[96:97], v[120:121], v[88:89]
	v_pk_mul_f32 v[98:99], v[124:125], v[86:87]
	global_store_dwordx4 v[94:95], v[72:75], off
	v_mul_f32_e32 v83, v83, v83
	v_mul_f32_e32 v85, v85, v85
	v_cvt_pk_bf16_f32 v72, v78, v79
	v_cvt_pk_bf16_f32 v73, v76, v77
	v_cvt_pk_bf16_f32 v74, v98, v99
	v_cvt_pk_bf16_f32 v75, v96, v97
	global_store_dwordx4 v[90:91], v[72:75], off
	global_load_dwordx4 v[72:75], v[92:93], off offset:512
	s_nop 0
	global_load_dwordx4 v[76:79], v[92:93], off offset:528
	v_mul_f32_e32 v87, v87, v87
	v_fmac_f32_e32 v83, v82, v82
	v_fmac_f32_e32 v85, v84, v84
	v_mul_f32_e32 v89, v89, v89
	v_fmac_f32_e32 v87, v86, v86
	v_add_f32_e32 v82, v83, v85
	v_fmac_f32_e32 v89, v88, v88
	v_add_f32_e32 v82, v87, v82
	v_add_f32_e32 v82, v89, v82
	s_waitcnt vmcnt(1)
	v_pk_fma_f32 v[70:71], v[70:71], v[168:169], v[74:75]
	v_pk_fma_f32 v[68:69], v[68:69], v[170:171], v[72:73]
	s_waitcnt vmcnt(0)
	v_pk_fma_f32 v[74:75], v[64:65], v[166:167], v[76:77]
	v_mul_f32_e32 v76, v69, v69
	v_mul_f32_e32 v77, v71, v71
	v_pk_fma_f32 v[72:73], v[66:67], v[164:165], v[78:79]
	v_cvt_pk_bf16_f32 v64, v68, v69
	v_mul_f32_e32 v78, v75, v75
	v_fmac_f32_e32 v76, v68, v68
	v_fmac_f32_e32 v77, v70, v70
	v_cvt_pk_bf16_f32 v65, v70, v71
	v_cvt_pk_bf16_f32 v66, v74, v75
	v_cvt_pk_bf16_f32 v67, v72, v73
	v_mul_f32_e32 v79, v73, v73
	global_store_dwordx4 v[94:95], v[64:67], off offset:256
	v_fmac_f32_e32 v78, v74, v74
	v_fmac_f32_e32 v79, v72, v72
	v_add_f32_e32 v64, v76, v77
	v_add_f32_e32 v64, v64, v78
	v_add_f32_e32 v64, v79, v64
	v_add_f32_e32 v67, v82, v64
	ds_bpermute_b32 v76, v179, v67
	v_pk_mul_f32 v[64:65], v[160:161], v[68:69]
	v_pk_mul_f32 v[68:69], v[158:159], v[74:75]
	v_cvt_pk_bf16_f32 v66, v64, v65
	v_pk_mul_f32 v[70:71], v[162:163], v[70:71]
	s_waitcnt lgkmcnt(0)
	v_add_f32_e32 v64, v67, v76
	ds_bpermute_b32 v65, v114, v64
	v_pk_mul_f32 v[72:73], v[156:157], v[72:73]
	v_cvt_pk_bf16_f32 v67, v70, v71
	v_cvt_pk_bf16_f32 v68, v68, v69
	s_nop 0
	v_cvt_pk_bf16_f32 v69, v72, v73
	global_store_dwordx4 v[90:91], v[66:69], off offset:256
	s_and_saveexec_b64 s[24:25], s[4:5]
	s_cbranch_execz .LBB0_597
	v_lshl_add_u64 v[66:67], v[80:81], 2, s[96:97]
	s_waitcnt lgkmcnt(0)
	v_add_f32_e32 v64, v64, v65
	global_atomic_add_f32 v[66:67], v64, off
.LBB0_597:
	s_or_b64 exec, exec, s[24:25]
	v_add_u32_e32 v64, 0x80, v146
	s_waitcnt lgkmcnt(0)
	v_ashrrev_i32_e32 v65, 31, v64
	v_lshlrev_b64 v[66:67], 10, v[64:65]
	v_lshl_add_u64 v[74:75], v[66:67], 0, v[144:145]
	v_lshl_add_u64 v[76:77], v[74:75], 2, s[52:53]
	global_load_dwordx4 v[66:69], v[76:77], off
	global_load_dwordx4 v[70:73], v[76:77], off offset:16
	v_lshlrev_b64 v[74:75], 1, v[74:75]
	v_lshl_add_u64 v[78:79], s[14:15], 0, v[74:75]
	v_lshl_add_u64 v[74:75], s[94:95], 0, v[74:75]
	s_waitcnt vmcnt(1)
	v_pk_fma_f32 v[68:69], v[62:63], v[150:151], v[68:69]
	v_pk_fma_f32 v[66:67], v[60:61], v[154:155], v[66:67]
	s_waitcnt vmcnt(0)
	v_pk_fma_f32 v[72:73], v[58:59], v[148:149], v[72:73]
	v_pk_fma_f32 v[70:71], v[56:57], v[152:153], v[70:71]
	v_cvt_pk_bf16_f32 v56, v66, v67
	v_cvt_pk_bf16_f32 v57, v68, v69
	v_pk_mul_f32 v[60:61], v[122:123], v[68:69]
	v_cvt_pk_bf16_f32 v58, v70, v71
	v_cvt_pk_bf16_f32 v59, v72, v73
	v_pk_mul_f32 v[62:63], v[126:127], v[66:67]
	v_pk_mul_f32 v[80:81], v[120:121], v[72:73]
	v_pk_mul_f32 v[82:83], v[124:125], v[70:71]
	global_store_dwordx4 v[78:79], v[56:59], off
	v_mul_f32_e32 v67, v67, v67
	v_mul_f32_e32 v69, v69, v69
	v_cvt_pk_bf16_f32 v56, v62, v63
	v_cvt_pk_bf16_f32 v57, v60, v61
	v_cvt_pk_bf16_f32 v58, v82, v83
	v_cvt_pk_bf16_f32 v59, v80, v81
	global_store_dwordx4 v[74:75], v[56:59], off
	global_load_dwordx4 v[56:59], v[76:77], off offset:512
	s_nop 0
	global_load_dwordx4 v[60:63], v[76:77], off offset:528
	v_mul_f32_e32 v71, v71, v71
	v_fmac_f32_e32 v67, v66, v66
	v_fmac_f32_e32 v69, v68, v68
	v_mul_f32_e32 v73, v73, v73
	v_fmac_f32_e32 v71, v70, v70
	v_add_f32_e32 v66, v67, v69
	v_fmac_f32_e32 v73, v72, v72
	v_add_f32_e32 v66, v66, v71
	v_add_f32_e32 v66, v73, v66
	s_waitcnt vmcnt(1)
	v_pk_fma_f32 v[54:55], v[54:55], v[168:169], v[58:59]
	v_pk_fma_f32 v[52:53], v[52:53], v[170:171], v[56:57]
	s_waitcnt vmcnt(0)
	v_pk_fma_f32 v[58:59], v[48:49], v[166:167], v[60:61]
	v_mul_f32_e32 v60, v53, v53
	v_mul_f32_e32 v61, v55, v55
	v_pk_fma_f32 v[56:57], v[50:51], v[164:165], v[62:63]
	v_cvt_pk_bf16_f32 v48, v52, v53
	v_mul_f32_e32 v62, v59, v59
	v_fmac_f32_e32 v60, v52, v52
	v_fmac_f32_e32 v61, v54, v54
	v_cvt_pk_bf16_f32 v49, v54, v55
	v_cvt_pk_bf16_f32 v50, v58, v59
	v_cvt_pk_bf16_f32 v51, v56, v57
	v_mul_f32_e32 v63, v57, v57
	global_store_dwordx4 v[78:79], v[48:51], off offset:256
	v_fmac_f32_e32 v62, v58, v58
	v_fmac_f32_e32 v63, v56, v56
	v_add_f32_e32 v48, v60, v61
	v_add_f32_e32 v48, v48, v62
	v_add_f32_e32 v48, v63, v48
	v_add_f32_e32 v51, v66, v48
	ds_bpermute_b32 v60, v179, v51
	v_pk_mul_f32 v[48:49], v[160:161], v[52:53]
	v_pk_mul_f32 v[52:53], v[158:159], v[58:59]
	v_cvt_pk_bf16_f32 v50, v48, v49
	v_pk_mul_f32 v[54:55], v[162:163], v[54:55]
	s_waitcnt lgkmcnt(0)
	v_add_f32_e32 v48, v51, v60
	ds_bpermute_b32 v49, v114, v48
	v_pk_mul_f32 v[56:57], v[156:157], v[56:57]
	v_cvt_pk_bf16_f32 v51, v54, v55
	v_cvt_pk_bf16_f32 v52, v52, v53
	s_nop 0
	v_cvt_pk_bf16_f32 v53, v56, v57
	global_store_dwordx4 v[74:75], v[50:53], off offset:256
	s_and_saveexec_b64 s[24:25], s[4:5]
	s_cbranch_execz .LBB0_599
	v_lshl_add_u64 v[50:51], v[64:65], 2, s[96:97]
	s_waitcnt lgkmcnt(0)
	v_add_f32_e32 v48, v48, v49
	global_atomic_add_f32 v[50:51], v48, off
.LBB0_599:
	s_or_b64 exec, exec, s[24:25]
	v_add_u32_e32 v48, 0x90, v146
	s_waitcnt lgkmcnt(0)
	v_ashrrev_i32_e32 v49, 31, v48
	v_lshlrev_b64 v[50:51], 10, v[48:49]
	v_lshl_add_u64 v[58:59], v[50:51], 0, v[144:145]
	v_lshl_add_u64 v[60:61], v[58:59], 2, s[52:53]
	global_load_dwordx4 v[50:53], v[60:61], off
	global_load_dwordx4 v[54:57], v[60:61], off offset:16
	v_lshlrev_b64 v[58:59], 1, v[58:59]
	v_lshl_add_u64 v[62:63], s[14:15], 0, v[58:59]
	v_lshl_add_u64 v[58:59], s[94:95], 0, v[58:59]
	s_waitcnt vmcnt(1)
	v_pk_fma_f32 v[52:53], v[46:47], v[150:151], v[52:53]
	v_pk_fma_f32 v[50:51], v[44:45], v[154:155], v[50:51]
	s_waitcnt vmcnt(0)
	v_pk_fma_f32 v[56:57], v[42:43], v[148:149], v[56:57]
	v_pk_fma_f32 v[54:55], v[40:41], v[152:153], v[54:55]
	v_cvt_pk_bf16_f32 v40, v50, v51
	v_cvt_pk_bf16_f32 v41, v52, v53
	v_pk_mul_f32 v[44:45], v[122:123], v[52:53]
	v_cvt_pk_bf16_f32 v42, v54, v55
	v_cvt_pk_bf16_f32 v43, v56, v57
	v_pk_mul_f32 v[46:47], v[126:127], v[50:51]
	v_pk_mul_f32 v[64:65], v[120:121], v[56:57]
	v_pk_mul_f32 v[66:67], v[124:125], v[54:55]
	global_store_dwordx4 v[62:63], v[40:43], off
	v_mul_f32_e32 v51, v51, v51
	v_mul_f32_e32 v53, v53, v53
	v_cvt_pk_bf16_f32 v40, v46, v47
	v_cvt_pk_bf16_f32 v41, v44, v45
	v_cvt_pk_bf16_f32 v42, v66, v67
	v_cvt_pk_bf16_f32 v43, v64, v65
	global_store_dwordx4 v[58:59], v[40:43], off
	global_load_dwordx4 v[40:43], v[60:61], off offset:512
	s_nop 0
	global_load_dwordx4 v[44:47], v[60:61], off offset:528
	v_mul_f32_e32 v55, v55, v55
	v_fmac_f32_e32 v51, v50, v50
	v_fmac_f32_e32 v53, v52, v52
	v_mul_f32_e32 v57, v57, v57
	v_fmac_f32_e32 v55, v54, v54
	v_add_f32_e32 v50, v51, v53
	v_fmac_f32_e32 v57, v56, v56
	v_add_f32_e32 v50, v55, v50
	v_add_f32_e32 v50, v57, v50
	s_waitcnt vmcnt(1)
	v_pk_fma_f32 v[38:39], v[38:39], v[168:169], v[42:43]
	v_pk_fma_f32 v[36:37], v[36:37], v[170:171], v[40:41]
	s_waitcnt vmcnt(0)
	v_pk_fma_f32 v[42:43], v[32:33], v[166:167], v[44:45]
	v_mul_f32_e32 v44, v37, v37
	v_mul_f32_e32 v45, v39, v39
	v_pk_fma_f32 v[40:41], v[34:35], v[164:165], v[46:47]
	v_cvt_pk_bf16_f32 v32, v36, v37
	v_mul_f32_e32 v46, v43, v43
	v_fmac_f32_e32 v44, v36, v36
	v_fmac_f32_e32 v45, v38, v38
	v_cvt_pk_bf16_f32 v33, v38, v39
	v_cvt_pk_bf16_f32 v34, v42, v43
	v_cvt_pk_bf16_f32 v35, v40, v41
	v_mul_f32_e32 v47, v41, v41
	global_store_dwordx4 v[62:63], v[32:35], off offset:256
	v_fmac_f32_e32 v46, v42, v42
	v_fmac_f32_e32 v47, v40, v40
	v_add_f32_e32 v32, v44, v45
	v_add_f32_e32 v32, v32, v46
	v_add_f32_e32 v32, v47, v32
	v_add_f32_e32 v35, v50, v32
	ds_bpermute_b32 v44, v179, v35
	v_pk_mul_f32 v[32:33], v[160:161], v[36:37]
	v_pk_mul_f32 v[36:37], v[158:159], v[42:43]
	v_cvt_pk_bf16_f32 v34, v32, v33
	v_pk_mul_f32 v[38:39], v[162:163], v[38:39]
	s_waitcnt lgkmcnt(0)
	v_add_f32_e32 v32, v35, v44
	ds_bpermute_b32 v33, v114, v32
	v_pk_mul_f32 v[40:41], v[156:157], v[40:41]
	v_cvt_pk_bf16_f32 v35, v38, v39
	v_cvt_pk_bf16_f32 v36, v36, v37
	s_nop 0
	v_cvt_pk_bf16_f32 v37, v40, v41
	global_store_dwordx4 v[58:59], v[34:37], off offset:256
	s_and_saveexec_b64 s[24:25], s[4:5]
	s_cbranch_execz .LBB0_601
	v_lshl_add_u64 v[34:35], v[48:49], 2, s[96:97]
	s_waitcnt lgkmcnt(0)
	v_add_f32_e32 v32, v32, v33
	global_atomic_add_f32 v[34:35], v32, off
.LBB0_601:
	s_or_b64 exec, exec, s[24:25]
	v_add_u32_e32 v32, 0xa0, v146
	s_waitcnt lgkmcnt(0)
	v_ashrrev_i32_e32 v33, 31, v32
	v_lshlrev_b64 v[34:35], 10, v[32:33]
	v_lshl_add_u64 v[42:43], v[34:35], 0, v[144:145]
	v_lshl_add_u64 v[44:45], v[42:43], 2, s[52:53]
	global_load_dwordx4 v[34:37], v[44:45], off
	global_load_dwordx4 v[38:41], v[44:45], off offset:16
	v_lshlrev_b64 v[42:43], 1, v[42:43]
	v_lshl_add_u64 v[46:47], s[14:15], 0, v[42:43]
	v_lshl_add_u64 v[42:43], s[94:95], 0, v[42:43]
	s_waitcnt vmcnt(1)
	v_pk_fma_f32 v[36:37], v[30:31], v[150:151], v[36:37]
	v_pk_fma_f32 v[34:35], v[28:29], v[154:155], v[34:35]
	s_waitcnt vmcnt(0)
	v_pk_fma_f32 v[40:41], v[26:27], v[148:149], v[40:41]
	v_pk_fma_f32 v[38:39], v[24:25], v[152:153], v[38:39]
	v_cvt_pk_bf16_f32 v24, v34, v35
	v_cvt_pk_bf16_f32 v25, v36, v37
	v_pk_mul_f32 v[28:29], v[122:123], v[36:37]
	v_cvt_pk_bf16_f32 v26, v38, v39
	v_cvt_pk_bf16_f32 v27, v40, v41
	v_pk_mul_f32 v[30:31], v[126:127], v[34:35]
	v_pk_mul_f32 v[48:49], v[120:121], v[40:41]
	v_pk_mul_f32 v[50:51], v[124:125], v[38:39]
	global_store_dwordx4 v[46:47], v[24:27], off
	v_mul_f32_e32 v35, v35, v35
	v_mul_f32_e32 v37, v37, v37
	v_cvt_pk_bf16_f32 v24, v30, v31
	v_cvt_pk_bf16_f32 v25, v28, v29
	v_cvt_pk_bf16_f32 v26, v50, v51
	v_cvt_pk_bf16_f32 v27, v48, v49
	global_store_dwordx4 v[42:43], v[24:27], off
	global_load_dwordx4 v[24:27], v[44:45], off offset:512
	s_nop 0
	global_load_dwordx4 v[28:31], v[44:45], off offset:528
	v_mul_f32_e32 v39, v39, v39
	v_fmac_f32_e32 v35, v34, v34
	v_fmac_f32_e32 v37, v36, v36
	v_mul_f32_e32 v41, v41, v41
	v_fmac_f32_e32 v39, v38, v38
	v_add_f32_e32 v34, v35, v37
	v_fmac_f32_e32 v41, v40, v40
	v_add_f32_e32 v34, v39, v34
	v_add_f32_e32 v34, v41, v34
	s_waitcnt vmcnt(1)
	v_pk_fma_f32 v[22:23], v[22:23], v[168:169], v[26:27]
	v_pk_fma_f32 v[20:21], v[20:21], v[170:171], v[24:25]
	s_waitcnt vmcnt(0)
	v_pk_fma_f32 v[26:27], v[16:17], v[166:167], v[28:29]
	v_mul_f32_e32 v28, v21, v21
	v_mul_f32_e32 v29, v23, v23
	v_pk_fma_f32 v[24:25], v[18:19], v[164:165], v[30:31]
	v_cvt_pk_bf16_f32 v16, v20, v21
	v_mul_f32_e32 v30, v27, v27
	v_fmac_f32_e32 v28, v20, v20
	v_fmac_f32_e32 v29, v22, v22
	v_cvt_pk_bf16_f32 v17, v22, v23
	v_cvt_pk_bf16_f32 v18, v26, v27
	v_cvt_pk_bf16_f32 v19, v24, v25
	v_mul_f32_e32 v31, v25, v25
	global_store_dwordx4 v[46:47], v[16:19], off offset:256
	v_fmac_f32_e32 v30, v26, v26
	v_fmac_f32_e32 v31, v24, v24
	v_add_f32_e32 v16, v28, v29
	v_add_f32_e32 v16, v16, v30
	v_add_f32_e32 v16, v31, v16
	v_add_f32_e32 v19, v34, v16
	ds_bpermute_b32 v28, v179, v19
	v_pk_mul_f32 v[16:17], v[160:161], v[20:21]
	v_pk_mul_f32 v[20:21], v[158:159], v[26:27]
	v_cvt_pk_bf16_f32 v18, v16, v17
	v_pk_mul_f32 v[22:23], v[162:163], v[22:23]
	s_waitcnt lgkmcnt(0)
	v_add_f32_e32 v16, v19, v28
	ds_bpermute_b32 v17, v114, v16
	v_pk_mul_f32 v[24:25], v[156:157], v[24:25]
	v_cvt_pk_bf16_f32 v19, v22, v23
	v_cvt_pk_bf16_f32 v20, v20, v21
	s_nop 0
	v_cvt_pk_bf16_f32 v21, v24, v25
	global_store_dwordx4 v[42:43], v[18:21], off offset:256
	s_and_saveexec_b64 s[24:25], s[4:5]
	s_cbranch_execz .LBB0_603
	v_lshl_add_u64 v[18:19], v[32:33], 2, s[96:97]
	s_waitcnt lgkmcnt(0)
	v_add_f32_e32 v16, v16, v17
	global_atomic_add_f32 v[18:19], v16, off
.LBB0_603:
	s_or_b64 exec, exec, s[24:25]
	v_add_u32_e32 v16, 0xb0, v146
	s_waitcnt lgkmcnt(0)
	v_ashrrev_i32_e32 v17, 31, v16
	v_lshlrev_b64 v[18:19], 10, v[16:17]
	v_lshl_add_u64 v[26:27], v[18:19], 0, v[144:145]
	v_lshl_add_u64 v[28:29], v[26:27], 2, s[52:53]
	global_load_dwordx4 v[18:21], v[28:29], off
	global_load_dwordx4 v[22:25], v[28:29], off offset:16
	v_lshlrev_b64 v[26:27], 1, v[26:27]
	v_lshl_add_u64 v[30:31], s[14:15], 0, v[26:27]
	v_lshl_add_u64 v[26:27], s[94:95], 0, v[26:27]
	s_waitcnt vmcnt(1)
	v_pk_fma_f32 v[20:21], v[14:15], v[150:151], v[20:21]
	v_pk_fma_f32 v[18:19], v[12:13], v[154:155], v[18:19]
	s_waitcnt vmcnt(0)
	v_pk_fma_f32 v[24:25], v[10:11], v[148:149], v[24:25]
	v_pk_fma_f32 v[22:23], v[8:9], v[152:153], v[22:23]
	v_cvt_pk_bf16_f32 v8, v18, v19
	v_cvt_pk_bf16_f32 v9, v20, v21
	v_pk_mul_f32 v[12:13], v[122:123], v[20:21]
	v_cvt_pk_bf16_f32 v10, v22, v23
	v_cvt_pk_bf16_f32 v11, v24, v25
	v_pk_mul_f32 v[14:15], v[126:127], v[18:19]
	v_pk_mul_f32 v[32:33], v[120:121], v[24:25]
	v_pk_mul_f32 v[34:35], v[124:125], v[22:23]
	global_store_dwordx4 v[30:31], v[8:11], off
	v_mul_f32_e32 v19, v19, v19
	v_mul_f32_e32 v21, v21, v21
	v_cvt_pk_bf16_f32 v8, v14, v15
	v_cvt_pk_bf16_f32 v9, v12, v13
	v_cvt_pk_bf16_f32 v10, v34, v35
	v_cvt_pk_bf16_f32 v11, v32, v33
	global_store_dwordx4 v[26:27], v[8:11], off
	global_load_dwordx4 v[8:11], v[28:29], off offset:512
	s_nop 0
	global_load_dwordx4 v[12:15], v[28:29], off offset:528
	v_mul_f32_e32 v23, v23, v23
	v_fmac_f32_e32 v19, v18, v18
	v_fmac_f32_e32 v21, v20, v20
	v_mul_f32_e32 v25, v25, v25
	v_fmac_f32_e32 v23, v22, v22
	v_add_f32_e32 v18, v19, v21
	v_fmac_f32_e32 v25, v24, v24
	v_add_f32_e32 v18, v23, v18
	v_add_f32_e32 v18, v25, v18
	s_waitcnt vmcnt(1)
	v_pk_fma_f32 v[6:7], v[6:7], v[168:169], v[10:11]
	v_pk_fma_f32 v[4:5], v[4:5], v[170:171], v[8:9]
	s_waitcnt vmcnt(0)
	v_pk_fma_f32 v[10:11], v[0:1], v[166:167], v[12:13]
	v_mul_f32_e32 v12, v5, v5
	v_mul_f32_e32 v13, v7, v7
	v_pk_fma_f32 v[8:9], v[2:3], v[164:165], v[14:15]
	v_cvt_pk_bf16_f32 v0, v4, v5
	v_mul_f32_e32 v14, v11, v11
	v_fmac_f32_e32 v12, v4, v4
	v_fmac_f32_e32 v13, v6, v6
	v_cvt_pk_bf16_f32 v1, v6, v7
	v_cvt_pk_bf16_f32 v2, v10, v11
	v_cvt_pk_bf16_f32 v3, v8, v9
	v_mul_f32_e32 v15, v9, v9
	global_store_dwordx4 v[30:31], v[0:3], off offset:256
	v_fmac_f32_e32 v14, v10, v10
	v_fmac_f32_e32 v15, v8, v8
	v_add_f32_e32 v0, v12, v13
	v_add_f32_e32 v0, v0, v14
	v_add_f32_e32 v0, v15, v0
	v_add_f32_e32 v3, v18, v0
	ds_bpermute_b32 v12, v179, v3
	v_pk_mul_f32 v[0:1], v[160:161], v[4:5]
	v_pk_mul_f32 v[4:5], v[158:159], v[10:11]
	v_cvt_pk_bf16_f32 v2, v0, v1
	v_pk_mul_f32 v[6:7], v[162:163], v[6:7]
	s_waitcnt lgkmcnt(0)
	v_add_f32_e32 v0, v3, v12
	ds_bpermute_b32 v1, v114, v0
	v_pk_mul_f32 v[8:9], v[156:157], v[8:9]
	v_cvt_pk_bf16_f32 v3, v6, v7
	v_cvt_pk_bf16_f32 v4, v4, v5
	s_nop 0
	v_cvt_pk_bf16_f32 v5, v8, v9
	global_store_dwordx4 v[26:27], v[2:5], off offset:256
	s_and_saveexec_b64 s[24:25], s[4:5]
	s_cbranch_execz .LBB0_605
	v_lshl_add_u64 v[2:3], v[16:17], 2, s[96:97]
	s_waitcnt lgkmcnt(0)
	v_add_f32_e32 v0, v0, v1
	global_atomic_add_f32 v[2:3], v0, off

.LBB0_809:
	s_and_b64 vcc, exec, s[0:1]
	s_mov_b64 s[0:1], -1
	s_ashr_i32 s26, s51, 31
	s_lshr_b32 s26, s26, 27
	s_add_i32 s26, s51, s26
	s_ashr_i32 s26, s26, 5
	s_mul_hi_i32 s27, s26, 0x6000
	s_mulk_i32 s26, 0x6000
	s_add_u32 s26, s42, s26
	s_addc_u32 s27, s43, s27
	v_lshl_add_u32 v156, s51, 8, v158
	v_lshl_or_b32 v252, s52, 8, v160
	v_lshlrev_b32_e32 v156, 11, v156
	v_lshl_add_u32 v156, v252, 1, v156
	v_lshlrev_b32_e32 v157, 1, v156
	v_lshlrev_b32_e32 v252, 2, v252
	global_load_dwordx4 v[228:231], v252, s[26:27]
	global_load_dwordx4 v[232:235], v252, s[26:27] offset:16
	global_load_dwordx4 v[236:239], v252, s[26:27] offset:512
	global_load_dwordx4 v[240:243], v252, s[26:27] offset:528
	global_load_dwordx4 v[244:247], v252, s[8:9]
	global_load_dwordx4 v[248:251], v252, s[8:9] offset:16
	global_load_dwordx4 v[144:147], v252, s[8:9] offset:512
	global_load_dwordx4 v[148:151], v252, s[8:9] offset:528
	s_mov_b32 s16, s14
	s_mov_b32 s17, s15
	global_load_dwordx4 v[164:167], v156, s[16:17]
	global_load_dwordx4 v[168:171], v156, s[16:17] offset:256
	s_add_u32 s16, s16, 0x8000
	s_addc_u32 s17, s17, 0
	global_load_dwordx4 v[172:175], v156, s[16:17]
	global_load_dwordx4 v[176:179], v156, s[16:17] offset:256
	s_add_u32 s16, s16, 0x8000
	s_addc_u32 s17, s17, 0
	global_load_dwordx4 v[180:183], v156, s[16:17]
	global_load_dwordx4 v[184:187], v156, s[16:17] offset:256
	s_add_u32 s16, s16, 0x8000
	s_addc_u32 s17, s17, 0
	global_load_dwordx4 v[188:191], v156, s[16:17]
	global_load_dwordx4 v[192:195], v156, s[16:17] offset:256
	s_add_u32 s16, s16, 0x28000
	s_addc_u32 s17, s17, 0
	global_load_dwordx4 v[196:199], v156, s[16:17]
	global_load_dwordx4 v[200:203], v156, s[16:17] offset:256
	s_add_u32 s16, s16, 0x8000
	s_addc_u32 s17, s17, 0
	global_load_dwordx4 v[204:207], v156, s[16:17]
	global_load_dwordx4 v[208:211], v156, s[16:17] offset:256
	s_add_u32 s16, s16, 0x8000
	s_addc_u32 s17, s17, 0
	global_load_dwordx4 v[212:215], v156, s[16:17]
	global_load_dwordx4 v[216:219], v156, s[16:17] offset:256
	s_add_u32 s16, s16, 0x8000
	s_addc_u32 s17, s17, 0
	global_load_dwordx4 v[220:223], v156, s[16:17]
	global_load_dwordx4 v[224:227], v156, s[16:17] offset:256
	s_mov_b32 s18, s86
	s_mov_b32 s19, s87
	s_waitcnt vmcnt(16)
	v_pk_add_f32 v[228:229], v[228:229], v[244:245]
	v_pk_add_f32 v[230:231], v[230:231], v[246:247]
	v_pk_add_f32 v[232:233], v[232:233], v[248:249]
	v_pk_add_f32 v[234:235], v[234:235], v[250:251]
	v_pk_add_f32 v[236:237], v[236:237], v[144:145]
	v_pk_add_f32 v[238:239], v[238:239], v[146:147]
	v_pk_add_f32 v[240:241], v[240:241], v[148:149]
	v_pk_add_f32 v[242:243], v[242:243], v[150:151]
	s_waitcnt vmcnt(15)
	v_lshlrev_b32_e32 v152, 16, v164
	v_and_b32_e32 v153, 0xffff0000, v164
	v_pk_fma_f32 v[124:125], v[124:125], v[228:229], v[152:153]
	v_lshlrev_b32_e32 v154, 16, v165
	v_and_b32_e32 v155, 0xffff0000, v165
	v_pk_fma_f32 v[126:127], v[126:127], v[230:231], v[154:155]
	v_lshlrev_b32_e32 v152, 16, v166
	v_and_b32_e32 v153, 0xffff0000, v166
	v_pk_fma_f32 v[120:121], v[120:121], v[232:233], v[152:153]
	v_lshlrev_b32_e32 v154, 16, v167
	v_and_b32_e32 v155, 0xffff0000, v167
	v_pk_fma_f32 v[122:123], v[122:123], v[234:235], v[154:155]
	global_store_dwordx4 v157, v[124:127], s[18:19]
	global_store_dwordx4 v157, v[120:123], s[18:19] offset:16
	s_waitcnt vmcnt(16)
	v_lshlrev_b32_e32 v152, 16, v168
	v_and_b32_e32 v153, 0xffff0000, v168
	v_pk_fma_f32 v[116:117], v[116:117], v[236:237], v[152:153]
	v_lshlrev_b32_e32 v154, 16, v169
	v_and_b32_e32 v155, 0xffff0000, v169
	v_pk_fma_f32 v[118:119], v[118:119], v[238:239], v[154:155]
	v_lshlrev_b32_e32 v152, 16, v170
	v_and_b32_e32 v153, 0xffff0000, v170
	v_pk_fma_f32 v[112:113], v[112:113], v[240:241], v[152:153]
	v_lshlrev_b32_e32 v154, 16, v171
	v_and_b32_e32 v155, 0xffff0000, v171
	v_pk_fma_f32 v[114:115], v[114:115], v[242:243], v[154:155]
	global_store_dwordx4 v157, v[116:119], s[18:19] offset:512
	global_store_dwordx4 v157, v[112:115], s[18:19] offset:528
	s_add_u32 s18, s18, 0x10000
	s_addc_u32 s19, s19, 0
	s_waitcnt vmcnt(17)
	v_lshlrev_b32_e32 v152, 16, v172
	v_and_b32_e32 v153, 0xffff0000, v172
	v_pk_fma_f32 v[108:109], v[108:109], v[228:229], v[152:153]
	v_lshlrev_b32_e32 v154, 16, v173
	v_and_b32_e32 v155, 0xffff0000, v173
	v_pk_fma_f32 v[110:111], v[110:111], v[230:231], v[154:155]
	v_lshlrev_b32_e32 v152, 16, v174
	v_and_b32_e32 v153, 0xffff0000, v174
	v_pk_fma_f32 v[104:105], v[104:105], v[232:233], v[152:153]
	v_lshlrev_b32_e32 v154, 16, v175
	v_and_b32_e32 v155, 0xffff0000, v175
	v_pk_fma_f32 v[106:107], v[106:107], v[234:235], v[154:155]
	global_store_dwordx4 v157, v[108:111], s[18:19]
	global_store_dwordx4 v157, v[104:107], s[18:19] offset:16
	s_waitcnt vmcnt(18)
	v_lshlrev_b32_e32 v152, 16, v176
	v_and_b32_e32 v153, 0xffff0000, v176
	v_pk_fma_f32 v[100:101], v[100:101], v[236:237], v[152:153]
	v_lshlrev_b32_e32 v154, 16, v177
	v_and_b32_e32 v155, 0xffff0000, v177
	v_pk_fma_f32 v[102:103], v[102:103], v[238:239], v[154:155]
	v_lshlrev_b32_e32 v152, 16, v178
	v_and_b32_e32 v153, 0xffff0000, v178
	v_pk_fma_f32 v[96:97], v[96:97], v[240:241], v[152:153]
	v_lshlrev_b32_e32 v154, 16, v179
	v_and_b32_e32 v155, 0xffff0000, v179
	v_pk_fma_f32 v[98:99], v[98:99], v[242:243], v[154:155]
	global_store_dwordx4 v157, v[100:103], s[18:19] offset:512
	global_store_dwordx4 v157, v[96:99], s[18:19] offset:528
	s_add_u32 s18, s18, 0x10000
	s_addc_u32 s19, s19, 0
	s_waitcnt vmcnt(19)
	v_lshlrev_b32_e32 v152, 16, v180
	v_and_b32_e32 v153, 0xffff0000, v180
	v_pk_fma_f32 v[92:93], v[92:93], v[228:229], v[152:153]
	v_lshlrev_b32_e32 v154, 16, v181
	v_and_b32_e32 v155, 0xffff0000, v181
	v_pk_fma_f32 v[94:95], v[94:95], v[230:231], v[154:155]
	v_lshlrev_b32_e32 v152, 16, v182
	v_and_b32_e32 v153, 0xffff0000, v182
	v_pk_fma_f32 v[88:89], v[88:89], v[232:233], v[152:153]
	v_lshlrev_b32_e32 v154, 16, v183
	v_and_b32_e32 v155, 0xffff0000, v183
	v_pk_fma_f32 v[90:91], v[90:91], v[234:235], v[154:155]
	global_store_dwordx4 v157, v[92:95], s[18:19]
	global_store_dwordx4 v157, v[88:91], s[18:19] offset:16
	s_waitcnt vmcnt(20)
	v_lshlrev_b32_e32 v152, 16, v184
	v_and_b32_e32 v153, 0xffff0000, v184
	v_pk_fma_f32 v[84:85], v[84:85], v[236:237], v[152:153]
	v_lshlrev_b32_e32 v154, 16, v185
	v_and_b32_e32 v155, 0xffff0000, v185
	v_pk_fma_f32 v[86:87], v[86:87], v[238:239], v[154:155]
	v_lshlrev_b32_e32 v152, 16, v186
	v_and_b32_e32 v153, 0xffff0000, v186
	v_pk_fma_f32 v[80:81], v[80:81], v[240:241], v[152:153]
	v_lshlrev_b32_e32 v154, 16, v187
	v_and_b32_e32 v155, 0xffff0000, v187
	v_pk_fma_f32 v[82:83], v[82:83], v[242:243], v[154:155]
	global_store_dwordx4 v157, v[84:87], s[18:19] offset:512
	global_store_dwordx4 v157, v[80:83], s[18:19] offset:528
	s_add_u32 s18, s18, 0x10000
	s_addc_u32 s19, s19, 0
	s_waitcnt vmcnt(21)
	v_lshlrev_b32_e32 v152, 16, v188
	v_and_b32_e32 v153, 0xffff0000, v188
	v_pk_fma_f32 v[76:77], v[76:77], v[228:229], v[152:153]
	v_lshlrev_b32_e32 v154, 16, v189
	v_and_b32_e32 v155, 0xffff0000, v189
	v_pk_fma_f32 v[78:79], v[78:79], v[230:231], v[154:155]
	v_lshlrev_b32_e32 v152, 16, v190
	v_and_b32_e32 v153, 0xffff0000, v190
	v_pk_fma_f32 v[72:73], v[72:73], v[232:233], v[152:153]
	v_lshlrev_b32_e32 v154, 16, v191
	v_and_b32_e32 v155, 0xffff0000, v191
	v_pk_fma_f32 v[74:75], v[74:75], v[234:235], v[154:155]
	global_store_dwordx4 v157, v[76:79], s[18:19]
	global_store_dwordx4 v157, v[72:75], s[18:19] offset:16
	s_waitcnt vmcnt(22)
	v_lshlrev_b32_e32 v152, 16, v192
	v_and_b32_e32 v153, 0xffff0000, v192
	v_pk_fma_f32 v[68:69], v[68:69], v[236:237], v[152:153]
	v_lshlrev_b32_e32 v154, 16, v193
	v_and_b32_e32 v155, 0xffff0000, v193
	v_pk_fma_f32 v[70:71], v[70:71], v[238:239], v[154:155]
	v_lshlrev_b32_e32 v152, 16, v194
	v_and_b32_e32 v153, 0xffff0000, v194
	v_pk_fma_f32 v[64:65], v[64:65], v[240:241], v[152:153]
	v_lshlrev_b32_e32 v154, 16, v195
	v_and_b32_e32 v155, 0xffff0000, v195
	v_pk_fma_f32 v[66:67], v[66:67], v[242:243], v[154:155]
	global_store_dwordx4 v157, v[68:71], s[18:19] offset:512
	global_store_dwordx4 v157, v[64:67], s[18:19] offset:528
	s_add_u32 s18, s18, 0x50000
	s_addc_u32 s19, s19, 0
	s_waitcnt vmcnt(23)
	v_lshlrev_b32_e32 v152, 16, v196
	v_and_b32_e32 v153, 0xffff0000, v196
	v_pk_fma_f32 v[60:61], v[60:61], v[228:229], v[152:153]
	v_lshlrev_b32_e32 v154, 16, v197
	v_and_b32_e32 v155, 0xffff0000, v197
	v_pk_fma_f32 v[62:63], v[62:63], v[230:231], v[154:155]
	v_lshlrev_b32_e32 v152, 16, v198
	v_and_b32_e32 v153, 0xffff0000, v198
	v_pk_fma_f32 v[56:57], v[56:57], v[232:233], v[152:153]
	v_lshlrev_b32_e32 v154, 16, v199
	v_and_b32_e32 v155, 0xffff0000, v199
	v_pk_fma_f32 v[58:59], v[58:59], v[234:235], v[154:155]
	global_store_dwordx4 v157, v[60:63], s[18:19]
	global_store_dwordx4 v157, v[56:59], s[18:19] offset:16
	s_waitcnt vmcnt(24)
	v_lshlrev_b32_e32 v152, 16, v200
	v_and_b32_e32 v153, 0xffff0000, v200
	v_pk_fma_f32 v[52:53], v[52:53], v[236:237], v[152:153]
	v_lshlrev_b32_e32 v154, 16, v201
	v_and_b32_e32 v155, 0xffff0000, v201
	v_pk_fma_f32 v[54:55], v[54:55], v[238:239], v[154:155]
	v_lshlrev_b32_e32 v152, 16, v202
	v_and_b32_e32 v153, 0xffff0000, v202
	v_pk_fma_f32 v[48:49], v[48:49], v[240:241], v[152:153]
	v_lshlrev_b32_e32 v154, 16, v203
	v_and_b32_e32 v155, 0xffff0000, v203
	v_pk_fma_f32 v[50:51], v[50:51], v[242:243], v[154:155]
	global_store_dwordx4 v157, v[52:55], s[18:19] offset:512
	global_store_dwordx4 v157, v[48:51], s[18:19] offset:528
	s_add_u32 s18, s18, 0x10000
	s_addc_u32 s19, s19, 0
	s_waitcnt vmcnt(25)
	v_lshlrev_b32_e32 v152, 16, v204
	v_and_b32_e32 v153, 0xffff0000, v204
	v_pk_fma_f32 v[44:45], v[44:45], v[228:229], v[152:153]
	v_lshlrev_b32_e32 v154, 16, v205
	v_and_b32_e32 v155, 0xffff0000, v205
	v_pk_fma_f32 v[46:47], v[46:47], v[230:231], v[154:155]
	v_lshlrev_b32_e32 v152, 16, v206
	v_and_b32_e32 v153, 0xffff0000, v206
	v_pk_fma_f32 v[40:41], v[40:41], v[232:233], v[152:153]
	v_lshlrev_b32_e32 v154, 16, v207
	v_and_b32_e32 v155, 0xffff0000, v207
	v_pk_fma_f32 v[42:43], v[42:43], v[234:235], v[154:155]
	global_store_dwordx4 v157, v[44:47], s[18:19]
	global_store_dwordx4 v157, v[40:43], s[18:19] offset:16
	s_waitcnt vmcnt(26)
	v_lshlrev_b32_e32 v152, 16, v208
	v_and_b32_e32 v153, 0xffff0000, v208
	v_pk_fma_f32 v[36:37], v[36:37], v[236:237], v[152:153]
	v_lshlrev_b32_e32 v154, 16, v209
	v_and_b32_e32 v155, 0xffff0000, v209
	v_pk_fma_f32 v[38:39], v[38:39], v[238:239], v[154:155]
	v_lshlrev_b32_e32 v152, 16, v210
	v_and_b32_e32 v153, 0xffff0000, v210
	v_pk_fma_f32 v[32:33], v[32:33], v[240:241], v[152:153]
	v_lshlrev_b32_e32 v154, 16, v211
	v_and_b32_e32 v155, 0xffff0000, v211
	v_pk_fma_f32 v[34:35], v[34:35], v[242:243], v[154:155]
	global_store_dwordx4 v157, v[36:39], s[18:19] offset:512
	global_store_dwordx4 v157, v[32:35], s[18:19] offset:528
	s_add_u32 s18, s18, 0x10000
	s_addc_u32 s19, s19, 0
	s_waitcnt vmcnt(27)
	v_lshlrev_b32_e32 v152, 16, v212
	v_and_b32_e32 v153, 0xffff0000, v212
	v_pk_fma_f32 v[28:29], v[28:29], v[228:229], v[152:153]
	v_lshlrev_b32_e32 v154, 16, v213
	v_and_b32_e32 v155, 0xffff0000, v213
	v_pk_fma_f32 v[30:31], v[30:31], v[230:231], v[154:155]
	v_lshlrev_b32_e32 v152, 16, v214
	v_and_b32_e32 v153, 0xffff0000, v214
	v_pk_fma_f32 v[24:25], v[24:25], v[232:233], v[152:153]
	v_lshlrev_b32_e32 v154, 16, v215
	v_and_b32_e32 v155, 0xffff0000, v215
	v_pk_fma_f32 v[26:27], v[26:27], v[234:235], v[154:155]
	global_store_dwordx4 v157, v[28:31], s[18:19]
	global_store_dwordx4 v157, v[24:27], s[18:19] offset:16
	s_waitcnt vmcnt(28)
	v_lshlrev_b32_e32 v152, 16, v216
	v_and_b32_e32 v153, 0xffff0000, v216
	v_pk_fma_f32 v[20:21], v[20:21], v[236:237], v[152:153]
	v_lshlrev_b32_e32 v154, 16, v217
	v_and_b32_e32 v155, 0xffff0000, v217
	v_pk_fma_f32 v[22:23], v[22:23], v[238:239], v[154:155]
	v_lshlrev_b32_e32 v152, 16, v218
	v_and_b32_e32 v153, 0xffff0000, v218
	v_pk_fma_f32 v[16:17], v[16:17], v[240:241], v[152:153]
	v_lshlrev_b32_e32 v154, 16, v219
	v_and_b32_e32 v155, 0xffff0000, v219
	v_pk_fma_f32 v[18:19], v[18:19], v[242:243], v[154:155]
	global_store_dwordx4 v157, v[20:23], s[18:19] offset:512
	global_store_dwordx4 v157, v[16:19], s[18:19] offset:528
	s_add_u32 s18, s18, 0x10000
	s_addc_u32 s19, s19, 0
	s_waitcnt vmcnt(29)
	v_lshlrev_b32_e32 v152, 16, v220
	v_and_b32_e32 v153, 0xffff0000, v220
	v_pk_fma_f32 v[12:13], v[12:13], v[228:229], v[152:153]
	v_lshlrev_b32_e32 v154, 16, v221
	v_and_b32_e32 v155, 0xffff0000, v221
	v_pk_fma_f32 v[14:15], v[14:15], v[230:231], v[154:155]
	v_lshlrev_b32_e32 v152, 16, v222
	v_and_b32_e32 v153, 0xffff0000, v222
	v_pk_fma_f32 v[8:9], v[8:9], v[232:233], v[152:153]
	v_lshlrev_b32_e32 v154, 16, v223
	v_and_b32_e32 v155, 0xffff0000, v223
	v_pk_fma_f32 v[10:11], v[10:11], v[234:235], v[154:155]
	global_store_dwordx4 v157, v[12:15], s[18:19]
	global_store_dwordx4 v157, v[8:11], s[18:19] offset:16
	s_waitcnt vmcnt(30)
	v_lshlrev_b32_e32 v152, 16, v224
	v_and_b32_e32 v153, 0xffff0000, v224
	v_pk_fma_f32 v[4:5], v[4:5], v[236:237], v[152:153]
	v_lshlrev_b32_e32 v154, 16, v225
	v_and_b32_e32 v155, 0xffff0000, v225
	v_pk_fma_f32 v[6:7], v[6:7], v[238:239], v[154:155]
	v_lshlrev_b32_e32 v152, 16, v226
	v_and_b32_e32 v153, 0xffff0000, v226
	v_pk_fma_f32 v[0:1], v[0:1], v[240:241], v[152:153]
	v_lshlrev_b32_e32 v154, 16, v227
	v_and_b32_e32 v155, 0xffff0000, v227
	v_pk_fma_f32 v[2:3], v[2:3], v[242:243], v[154:155]
	global_store_dwordx4 v157, v[4:7], s[18:19] offset:512
	global_store_dwordx4 v157, v[0:3], s[18:19] offset:528
	s_cbranch_vccnz .LBB0_794
	s_andn2_b64 vcc, exec, s[6:7]
	s_cbranch_vccnz .LBB0_793
	s_barrier
	s_branch .LBB0_793
